# CM: CL + 2208 layer-1 expert transposes tiles moved from P0b into the layer-1 mixer-phase tail (deferred-chunk queue reused for l=1)
# baseline (speedup 1.0000x reference)
; __device__ __forceinline__ TrJob tr_decode(const Params& p, char* ws, int job) {
;   TrJob t;
;   int l = job / TJ_PER_LAYER, rj = job % TJ_PER_LAYER;
;   if (rj < 640) {
;     t.src = p.w_in + (size_t)l * 1024 * 2560; t.K = 1024; t.N = 2560; t.kt = rj / 40; t.nt = rj % 40;
;     t.dst = (u16*)(ws + OFF_WINT) + (size_t)l * 2560 * 1024; t.mode = 0;
;   } else if (rj < 896) {
;     rj -= 640;
;     t.src = p.w_out + (size_t)l * 1024 * 1024; t.K = 1024; t.N = 1024; t.kt = rj / 16; t.nt = rj % 16;
;     t.dst = (u16*)(ws + OFF_WOUTT) + (size_t)l * 1024 * 1024; t.mode = 0;
;   } else {
;     rj -= 896;
;     int e = rj / 1536, q = rj % 1536;
;     size_t eo = (size_t)(l * 16 + e);
;     if (q < 512) {
;       t.src = p.w_gate + eo * 1024 * 2048; t.K = 1024; t.N = 2048; t.kt = q / 32; t.nt = q % 32;
;       t.dst = (u16*)(ws + OFF_WGUT) + eo * 4096 * 1024; t.mode = 1;
;     } else if (q < 1024) {
;       q -= 512;
;       t.src = p.w_up + eo * 1024 * 2048; t.K = 1024; t.N = 2048; t.kt = q / 32; t.nt = q % 32;
;       t.dst = (u16*)(ws + OFF_WGUT) + eo * 4096 * 1024; t.mode = 2;
;     } else {
;       q -= 1024;
;       t.src = p.w_down + eo * 2048 * 1024; t.K = 2048; t.N = 1024; t.kt = q / 16; t.nt = q % 16;
;       t.dst = (u16*)(ws + OFF_WDT) + eo * 1024 * 2048; t.mode = 0;
;     }
;   }
; __device__ __forceinline__ void p0_transposes(const Params& p, char* smem, int bid, int nb, int jlo, int jhi) {
;     ...
;   for (; j < jhi; j += 2 * nb) {
;     const int jn = j + 2 * nb;
;     if (jn < jhi) { tr_load(p, ws, jn, tid, n0); tr_load(p, ws, jn + 1, tid, n1); }
.LBB0_174:
	s_add_i32 s96, s97, s75
	s_cmp_gt_i32 s96, 0x670f
	s_cselect_b64 s[0:1], -1, 0
	s_and_b64 vcc, exec, s[0:1]
	s_cbranch_vccnz .LBB0_208
	s_mul_hi_i32 s10, s96, 0x5254e78f
	s_lshr_b32 s11, s10, 31
	s_ashr_i32 s10, s10, 13
	s_add_i32 s52, s10, s11
	s_mul_i32 s10, s52, 0xffff9c80
	s_add_i32 s10, s96, s10
	s_cmpk_gt_i32 s10, 0x27f
	s_mov_b64 s[58:59], -1
	s_cbranch_scc0 .LBB0_189
	s_cmpk_gt_u32 s10, 0x37f
	s_cbranch_scc0 .LBB0_186
	s_add_i32 s11, s10, 0xfc80
	s_and_b32 s33, s11, 0xffff
	s_mul_i32 s33, s33, 0xaaab
	s_lshr_b32 s33, s33, 26
	s_mul_i32 s40, s33, 0x600
	s_sub_i32 s11, s11, s40
	s_and_b32 s40, s11, 0xffff
	s_lshl_b32 s11, s52, 4
	s_add_i32 s54, s11, s33
	s_ashr_i32 s55, s54, 31
	s_lshl_b64 s[58:59], s[54:55], 23
	s_cmpk_gt_u32 s40, 0x1ff
	s_mov_b64 s[60:61], -1
	s_cbranch_scc0 .LBB0_183
	s_cmpk_gt_u32 s40, 0x3ff
	s_mov_b64 s[56:57], -1
	s_cbranch_scc0 .LBB0_180
	v_readlane_b32 s12, v238, 25
	s_add_i32 s11, s40, 0xfffffc00
	v_readlane_b32 s18, v238, 31
	v_readlane_b32 s19, v238, 32
	s_add_u32 s54, s18, s58
	v_readlane_b32 s13, v238, 26
	v_readlane_b32 s14, v238, 27
	v_readlane_b32 s15, v238, 28
	v_readlane_b32 s16, v238, 29
	v_readlane_b32 s17, v238, 30
	s_addc_u32 s55, s19, s59
	s_lshr_b32 s33, s11, 4
	s_and_b32 s11, s40, 15
	s_mov_b64 s[56:57], 0

; __global__ void __launch_bounds__(256, 2) fwd_megakernel(Params p) {
;     ...
;               if (l != 0 || rep != 0) break;
;               int j = atomicAdd((int*)(ws + OFF_CNT) + 16, 1);
;               if (j < TR_DEFER / TR_CHUNK) job = -2 - j;
;               break;
;             }
;           }
;           s_job = job;
.LBB0_696:
	s_andn2_saveexec_b64 s[4:5], s[10:11]
	s_cbranch_execz .LBB0_700
	v_readlane_b32 s10, v237, 29
	v_readlane_b32 s11, v237, 30
	v_mov_b32_e32 v3, -1
	s_andn2_b64 vcc, exec, s[10:11]
	s_cbranch_vccnz .Lp2d_l1
	v_readlane_b32 s10, v237, 23
	v_readlane_b32 s11, v237, 24
	s_movk_i32 s2, 0x140
	s_nop 0
	v_mov_b64_e32 v[2:3], s[10:11]
	global_atomic_add v2, v[2:3], v198, off sc0
	s_waitcnt vmcnt(0) lgkmcnt(0)
	v_sub_u32_e32 v3, -2, v2
	v_cmp_gt_i32_e32 vcc, s2, v2
	s_nop 1
	v_cndmask_b32_e32 v3, -1, v3, vcc
	s_branch .LBB0_699
.Lp2d_l1:
	v_readlane_b32 s10, v237, 23
	v_readlane_b32 s11, v237, 24
	s_movk_i32 s2, 69
	s_nop 0
	v_mov_b64_e32 v[2:3], s[10:11]
	global_atomic_add v2, v[2:3], v198, off offset:16 sc0
	s_waitcnt vmcnt(0) lgkmcnt(0)
	v_sub_u32_e32 v3, -2, v2
	v_cmp_gt_i32_e32 vcc, s2, v2
	s_nop 1
	v_cndmask_b32_e32 v3, -1, v3, vcc

; __device__ __forceinline__ TrJob tr_decode(const Params& p, char* ws, int job) {
;   TrJob t;
;   int l = job / TJ_PER_LAYER, rj = job % TJ_PER_LAYER;
;   if (rj < 640) {
;     t.src = p.w_in + (size_t)l * 1024 * 2560; t.K = 1024; t.N = 2560; t.kt = rj / 40; t.nt = rj % 40;
;     t.dst = (u16*)(ws + OFF_WINT) + (size_t)l * 2560 * 1024; t.mode = 0;
;   } else if (rj < 896) {
;     rj -= 640;
;     t.src = p.w_out + (size_t)l * 1024 * 1024; t.K = 1024; t.N = 1024; t.kt = rj / 16; t.nt = rj % 16;
;     t.dst = (u16*)(ws + OFF_WOUTT) + (size_t)l * 1024 * 1024; t.mode = 0;
;   } else {
;     rj -= 896;
;     int e = rj / 1536, q = rj % 1536;
;     size_t eo = (size_t)(l * 16 + e);
;     if (q < 512) {
;       t.src = p.w_gate + eo * 1024 * 2048; t.K = 1024; t.N = 2048; t.kt = q / 32; t.nt = q % 32;
;       t.dst = (u16*)(ws + OFF_WGUT) + eo * 4096 * 1024; t.mode = 1;
;     } else if (q < 1024) {
;       q -= 512;
;       t.src = p.w_up + eo * 1024 * 2048; t.K = 1024; t.N = 2048; t.kt = q / 32; t.nt = q % 32;
;       t.dst = (u16*)(ws + OFF_WGUT) + eo * 4096 * 1024; t.mode = 2;
;     } else {
;       q -= 1024;
;       t.src = p.w_down + eo * 2048 * 1024; t.K = 2048; t.N = 1024; t.kt = q / 16; t.nt = q % 16;
;       t.dst = (u16*)(ws + OFF_WDT) + eo * 1024 * 2048; t.mode = 0;
;     }
;   }
; __global__ void __launch_bounds__(256, 2) fwd_megakernel(Params p) {
;     ...
;         if (job < -1) {
;           const int c0_ = J_DEFER + (-2 - job) * TR_CHUNK;
;           p0_transposes(p, smem, 0, 1, c0_, c0_ + TR_CHUNK);
;           continue;
.LBB0_716:
	s_lshl_b32 s20, s10, 5
	v_readlane_b32 s22, v237, 29
	s_mov_b32 s2, 0x9ec0
	s_mov_b32 s100, 26320
	s_cmp_lg_u32 s22, 0
	s_cselect_b32 s2, s2, s100
	s_sub_i32 s22, s2, s20
	s_add_i32 s2, s22, 32
	s_cmp_lt_i32 s22, s2
	v_mov_b32_e32 v2, v172
	s_mov_b64 s[0:1], s[58:59]
	s_cselect_b64 s[4:5], -1, 0
	s_cmp_ge_i32 s22, s2
	s_cbranch_scc1 .LBB0_750
	s_mul_hi_i32 s10, s22, 0x5254e78f
	s_lshr_b32 s11, s10, 31
	s_ashr_i32 s10, s10, 13
	s_add_i32 s10, s10, s11
	s_mul_i32 s11, s10, 0x6380
	s_sub_i32 s21, s22, s11
	s_cmpk_gt_i32 s21, 0x27f
	s_mov_b64 s[16:17], -1
	s_cbranch_scc0 .LBB0_731
	s_cmpk_gt_u32 s21, 0x37f
	s_cbranch_scc0 .LBB0_728
	s_add_i32 s11, s21, 0xfc80
	s_and_b32 s12, s11, 0xffff
	s_mul_i32 s12, s12, 0xaaab
	s_lshr_b32 s12, s12, 26
	s_mul_i32 s13, s12, 0x600
	s_sub_i32 s11, s11, s13
	s_and_b32 s24, s11, 0xffff
	s_lshl_b32 s11, s10, 4
	s_add_i32 s16, s11, s12
	s_ashr_i32 s17, s16, 31
	s_cmpk_gt_u32 s24, 0x1ff
	s_mov_b64 s[18:19], -1
	s_cbranch_scc0 .LBB0_725
	s_lshl_b64 s[18:19], s[16:17], 23
	s_cmpk_gt_u32 s24, 0x3ff
	s_mov_b64 s[14:15], -1
	s_cbranch_scc0 .LBB0_722
	v_readlane_b32 s40, v238, 25
	s_add_i32 s11, s24, 0xfffffc00
	v_readlane_b32 s46, v238, 31
	v_readlane_b32 s47, v238, 32
	s_add_u32 s12, s46, s18
	v_readlane_b32 s41, v238, 26
	v_readlane_b32 s42, v238, 27
	v_readlane_b32 s43, v238, 28
	v_readlane_b32 s44, v238, 29
	v_readlane_b32 s45, v238, 30
	s_addc_u32 s13, s47, s19
	s_lshr_b32 s23, s11, 4
	s_and_b32 s11, s24, 15
	s_mov_b64 s[14:15], 0
